# E1: prompt-FoX QK K-fragment ds_read software pipelining (distinct regs, counted lgkmcnt)
# baseline (speedup 1.0000x reference)
.LBB0_1390:
	s_cmp_le_i32 s16, s15
	s_cselect_b64 s[20:21], -1, 0
	s_and_b64 s[20:21], s[84:85], s[20:21]
	s_andn2_b64 vcc, exec, s[20:21]
	s_cbranch_vccnz .LBB0_1396
	s_bitcmp1_b32 s18, 0
	s_cselect_b32 s18, 0xa800, 0
	s_add_i32 s70, s18, 0
	ds_read_b128 v[82:85], v198
	ds_read_b128 v[86:89], v198 offset:32
	ds_read_b128 v[90:93], v198 offset:64
	ds_read_b128 v[94:97], v198 offset:96
	v_add3_u32 v2, s70, v214, v186
	ds_read_b128 v[226:229], v2
	ds_read_b128 v[230:233], v2 offset:32
	ds_read_b128 v[234:237], v2 offset:64
	ds_read_b128 v[238:241], v2 offset:96
	ds_read_b128 v[50:53], v198 offset:128
	ds_read_b128 v[54:57], v198 offset:160
	ds_read_b128 v[58:61], v198 offset:192
	ds_read_b128 v[62:65], v198 offset:224
	s_add_i32 s18, s16, 0x7f
	s_cmp_le_i32 s18, s13
	s_waitcnt lgkmcnt(7)
	v_mfma_f32_32x32x16_bf16 v[82:97], v[226:229], v[114:117], v[82:97]
	ds_read_b128 v[4:7], v2 offset:4608
	s_waitcnt lgkmcnt(7)
	v_mfma_f32_32x32x16_bf16 v[82:97], v[230:233], v[118:121], v[82:97]
	ds_read_b128 v[8:11], v2 offset:4640
	s_waitcnt lgkmcnt(7)
	v_mfma_f32_32x32x16_bf16 v[82:97], v[234:237], v[122:125], v[82:97]
	ds_read_b128 v[12:15], v2 offset:4672
	s_waitcnt lgkmcnt(7)
	v_mfma_f32_32x32x16_bf16 v[82:97], v[238:241], v[126:129], v[82:97]
	ds_read_b128 v[160:163], v2 offset:4704
	ds_read_b128 v[66:69], v198 offset:256
	ds_read_b128 v[70:73], v198 offset:288
	ds_read_b128 v[74:77], v198 offset:320
	ds_read_b128 v[78:81], v198 offset:352
	s_waitcnt lgkmcnt(7)
	v_mfma_f32_32x32x16_bf16 v[50:65], v[4:7], v[114:117], v[50:65]
	ds_read_b128 v[226:229], v2 offset:9216
	s_waitcnt lgkmcnt(7)
	v_mfma_f32_32x32x16_bf16 v[50:65], v[8:11], v[118:121], v[50:65]
	ds_read_b128 v[230:233], v2 offset:9248
	s_waitcnt lgkmcnt(7)
	v_mfma_f32_32x32x16_bf16 v[50:65], v[12:15], v[122:125], v[50:65]
	ds_read_b128 v[234:237], v2 offset:9280
	s_waitcnt lgkmcnt(7)
	v_mfma_f32_32x32x16_bf16 v[50:65], v[160:163], v[126:129], v[50:65]
	ds_read_b128 v[238:241], v2 offset:9312
	ds_read_b128 v[98:101], v198 offset:384
	ds_read_b128 v[102:105], v198 offset:416
	ds_read_b128 v[106:109], v198 offset:448
	ds_read_b128 v[110:113], v198 offset:480
	s_waitcnt lgkmcnt(7)
	v_mfma_f32_32x32x16_bf16 v[66:81], v[226:229], v[114:117], v[66:81]
	ds_read_b128 v[4:7], v2 offset:13824
	s_waitcnt lgkmcnt(7)
	v_mfma_f32_32x32x16_bf16 v[66:81], v[230:233], v[118:121], v[66:81]
	ds_read_b128 v[8:11], v2 offset:13856
	s_waitcnt lgkmcnt(7)
	v_mfma_f32_32x32x16_bf16 v[66:81], v[234:237], v[122:125], v[66:81]
	ds_read_b128 v[12:15], v2 offset:13888
	s_waitcnt lgkmcnt(7)
	v_mfma_f32_32x32x16_bf16 v[66:81], v[238:241], v[126:129], v[66:81]
	ds_read_b128 v[160:163], v2 offset:13920
	s_waitcnt lgkmcnt(3)
	v_mfma_f32_32x32x16_bf16 v[98:113], v[4:7], v[114:117], v[98:113]
	s_waitcnt lgkmcnt(2)
	v_mfma_f32_32x32x16_bf16 v[98:113], v[8:11], v[118:121], v[98:113]
	s_waitcnt lgkmcnt(1)
	v_mfma_f32_32x32x16_bf16 v[98:113], v[12:15], v[122:125], v[98:113]
	s_waitcnt lgkmcnt(0)
	v_mfma_f32_32x32x16_bf16 v[98:113], v[160:163], v[126:129], v[98:113]
	s_cbranch_scc1 .LBB0_1393
	v_cmp_gt_i32_e64 s[46:47], 26, v195
	v_cmp_gt_i32_e64 s[48:49], 27, v195
	v_cmp_gt_i32_e64 s[44:45], 25, v195
	s_and_b64 s[46:47], s[48:49], s[46:47]
	v_cmp_gt_i32_e64 s[42:43], 24, v195
	v_cndmask_b32_e64 v97, v97, v190, s[48:49]
	v_cndmask_b32_e64 v96, v96, v190, s[46:47]
	s_and_b64 s[44:45], s[46:47], s[44:45]
	v_cmp_gt_i32_e64 s[46:47], 58, v195
	v_cmp_gt_i32_e64 s[48:49], 59, v195
	v_cmp_gt_i32_e64 s[40:41], 19, v195
	v_cndmask_b32_e64 v95, v95, v190, s[44:45]
	s_and_b64 s[42:43], s[44:45], s[42:43]
	v_cmp_gt_i32_e64 s[44:45], 57, v195
	s_and_b64 s[46:47], s[48:49], s[46:47]
	v_cmp_gt_i32_e64 s[38:39], 18, v195
	v_cndmask_b32_e64 v94, v94, v190, s[42:43]
	s_and_b64 s[40:41], s[42:43], s[40:41]
	v_cmp_gt_i32_e64 s[42:43], 56, v195
	v_cndmask_b32_e64 v65, v65, v190, s[48:49]
	v_cndmask_b32_e64 v64, v64, v190, s[46:47]
	s_and_b64 s[44:45], s[46:47], s[44:45]
	s_movk_i32 s46, 0x5a
	s_movk_i32 s48, 0x5b
	v_cmp_gt_i32_e64 s[36:37], 17, v195
	v_cndmask_b32_e64 v93, v93, v190, s[40:41]
	s_and_b64 s[38:39], s[40:41], s[38:39]
	v_cmp_gt_i32_e64 s[40:41], 51, v195
	v_cndmask_b32_e64 v63, v63, v190, s[44:45]
	s_and_b64 s[42:43], s[44:45], s[42:43]
	s_movk_i32 s44, 0x59
	v_cmp_gt_i32_e64 s[46:47], s46, v195
	v_cmp_gt_i32_e64 s[48:49], s48, v195
	v_cmp_gt_i32_e64 s[34:35], 16, v195
	v_cndmask_b32_e64 v92, v92, v190, s[38:39]
	s_and_b64 s[36:37], s[38:39], s[36:37]
	v_cmp_gt_i32_e64 s[38:39], 50, v195
	v_cndmask_b32_e64 v62, v62, v190, s[42:43]
	s_and_b64 s[40:41], s[42:43], s[40:41]
	s_movk_i32 s42, 0x58
	v_cmp_gt_i32_e64 s[44:45], s44, v195
	s_and_b64 s[46:47], s[48:49], s[46:47]
	v_cmp_gt_i32_e64 s[30:31], 11, v195
	v_cndmask_b32_e64 v91, v91, v190, s[36:37]
	s_and_b64 s[34:35], s[36:37], s[34:35]
	v_cmp_gt_i32_e64 s[36:37], 49, v195
	v_cndmask_b32_e64 v61, v61, v190, s[40:41]
	s_and_b64 s[38:39], s[40:41], s[38:39]
	s_movk_i32 s40, 0x53
	v_cmp_gt_i32_e64 s[42:43], s42, v195
	s_and_b64 s[44:45], s[46:47], s[44:45]
	v_cmp_gt_i32_e64 s[28:29], 10, v195
	v_cndmask_b32_e64 v90, v90, v190, s[34:35]
	s_and_b64 s[30:31], s[34:35], s[30:31]
	v_cmp_gt_i32_e64 s[34:35], 48, v195
	v_cndmask_b32_e64 v60, v60, v190, s[38:39]
	s_and_b64 s[36:37], s[38:39], s[36:37]
	s_movk_i32 s38, 0x52
	v_cmp_gt_i32_e64 s[40:41], s40, v195
	v_cndmask_b32_e64 v81, v81, v190, s[48:49]
	v_cndmask_b32_e64 v80, v80, v190, s[46:47]
	s_and_b64 s[42:43], s[44:45], s[42:43]
	s_movk_i32 s46, 0x7a
	s_movk_i32 s48, 0x7b
	v_cmp_gt_i32_e64 s[26:27], 9, v195
	v_cndmask_b32_e64 v89, v89, v190, s[30:31]
	s_and_b64 s[28:29], s[30:31], s[28:29]
	v_cmp_gt_i32_e64 s[30:31], 43, v195
	v_cndmask_b32_e64 v59, v59, v190, s[36:37]
	s_and_b64 s[34:35], s[36:37], s[34:35]
	s_movk_i32 s36, 0x51
	v_cmp_gt_i32_e64 s[38:39], s38, v195
	v_cndmask_b32_e64 v79, v79, v190, s[44:45]
	s_and_b64 s[40:41], s[42:43], s[40:41]
	s_movk_i32 s44, 0x79
	v_cmp_gt_i32_e64 s[46:47], s46, v195
	v_cmp_gt_i32_e64 s[48:49], s48, v195
	v_cmp_gt_i32_e64 s[24:25], 8, v195
	v_cndmask_b32_e64 v88, v88, v190, s[28:29]
	s_and_b64 s[26:27], s[28:29], s[26:27]
	v_cmp_gt_i32_e64 s[28:29], 42, v195
	v_cndmask_b32_e64 v58, v58, v190, s[34:35]
	s_and_b64 s[30:31], s[34:35], s[30:31]
	s_movk_i32 s34, 0x50
	v_cmp_gt_i32_e64 s[36:37], s36, v195
	v_cndmask_b32_e64 v78, v78, v190, s[42:43]
	s_and_b64 s[38:39], s[40:41], s[38:39]
	s_movk_i32 s42, 0x78
	v_cmp_gt_i32_e64 s[44:45], s44, v195
	s_and_b64 s[46:47], s[48:49], s[46:47]
	v_cmp_gt_i32_e64 s[22:23], 3, v195
	v_cndmask_b32_e64 v87, v87, v190, s[26:27]
	s_and_b64 s[24:25], s[26:27], s[24:25]
	v_cmp_gt_i32_e64 s[26:27], 41, v195
	v_cndmask_b32_e64 v57, v57, v190, s[30:31]
	s_and_b64 s[28:29], s[30:31], s[28:29]
	s_movk_i32 s30, 0x4b
	v_cmp_gt_i32_e64 s[34:35], s34, v195
	v_cndmask_b32_e64 v77, v77, v190, s[40:41]
	s_and_b64 s[36:37], s[38:39], s[36:37]
	s_movk_i32 s40, 0x73
	v_cmp_gt_i32_e64 s[42:43], s42, v195
	s_and_b64 s[44:45], s[46:47], s[44:45]
	v_cmp_gt_i32_e64 s[20:21], 2, v195
	v_cndmask_b32_e64 v86, v86, v190, s[24:25]
	s_and_b64 s[22:23], s[24:25], s[22:23]
	v_cmp_gt_i32_e64 s[24:25], 40, v195
	v_cndmask_b32_e64 v56, v56, v190, s[28:29]
	s_and_b64 s[26:27], s[28:29], s[26:27]
	s_movk_i32 s28, 0x4a
	v_cmp_gt_i32_e64 s[30:31], s30, v195
	v_cndmask_b32_e64 v76, v76, v190, s[38:39]
	s_and_b64 s[34:35], s[36:37], s[34:35]
	s_movk_i32 s38, 0x72
	v_cmp_gt_i32_e64 s[40:41], s40, v195
	s_and_b64 s[42:43], s[44:45], s[42:43]
	v_cmp_gt_i32_e64 s[18:19], 1, v195
	v_cndmask_b32_e64 v85, v85, v190, s[22:23]
	s_and_b64 s[20:21], s[22:23], s[20:21]
	v_cmp_gt_i32_e64 s[22:23], 35, v195
	v_cndmask_b32_e64 v55, v55, v190, s[26:27]
	s_and_b64 s[24:25], s[26:27], s[24:25]
	s_movk_i32 s26, 0x49
	v_cmp_gt_i32_e64 s[28:29], s28, v195
	v_cndmask_b32_e64 v75, v75, v190, s[36:37]
	s_and_b64 s[30:31], s[34:35], s[30:31]
	s_movk_i32 s36, 0x71
	v_cmp_gt_i32_e64 s[38:39], s38, v195
	s_and_b64 s[40:41], s[42:43], s[40:41]
	v_cmp_gt_i32_e32 vcc, 0, v195
	v_cndmask_b32_e64 v84, v84, v190, s[20:21]
	s_and_b64 s[18:19], s[20:21], s[18:19]
	v_cmp_gt_i32_e64 s[20:21], 34, v195
	v_cndmask_b32_e64 v54, v54, v190, s[24:25]
	s_and_b64 s[22:23], s[24:25], s[22:23]
	s_movk_i32 s24, 0x48
	v_cmp_gt_i32_e64 s[26:27], s26, v195
	v_cndmask_b32_e64 v74, v74, v190, s[34:35]
	s_and_b64 s[28:29], s[30:31], s[28:29]
	s_movk_i32 s34, 0x70
	v_cmp_gt_i32_e64 s[36:37], s36, v195
	s_and_b64 s[38:39], s[40:41], s[38:39]
	v_cndmask_b32_e64 v83, v83, v190, s[18:19]
	s_and_b64 vcc, s[18:19], vcc
	v_cmp_gt_i32_e64 s[18:19], 33, v195
	v_cndmask_b32_e64 v53, v53, v190, s[22:23]
	s_and_b64 s[20:21], s[22:23], s[20:21]
	s_movk_i32 s22, 0x43
	v_cmp_gt_i32_e64 s[24:25], s24, v195
	v_cndmask_b32_e64 v73, v73, v190, s[30:31]
	s_and_b64 s[26:27], s[28:29], s[26:27]
	s_movk_i32 s30, 0x6b
	v_cmp_gt_i32_e64 s[34:35], s34, v195
	s_and_b64 s[36:37], s[38:39], s[36:37]
	v_cndmask_b32_e32 v82, v82, v190, vcc
	v_cmp_gt_i32_e32 vcc, 32, v195
	v_cndmask_b32_e64 v52, v52, v190, s[20:21]
	s_and_b64 s[18:19], s[20:21], s[18:19]
	s_movk_i32 s20, 0x42
	v_cmp_gt_i32_e64 s[22:23], s22, v195
	v_cndmask_b32_e64 v72, v72, v190, s[28:29]
	s_and_b64 s[24:25], s[26:27], s[24:25]
	s_movk_i32 s28, 0x6a
	v_cmp_gt_i32_e64 s[30:31], s30, v195
	s_and_b64 s[34:35], s[36:37], s[34:35]
	v_cndmask_b32_e64 v51, v51, v190, s[18:19]
	s_and_b64 vcc, s[18:19], vcc
	s_movk_i32 s18, 0x41
	v_cmp_gt_i32_e64 s[20:21], s20, v195
	v_cndmask_b32_e64 v71, v71, v190, s[26:27]
	s_and_b64 s[22:23], s[24:25], s[22:23]
	s_movk_i32 s26, 0x69
	v_cmp_gt_i32_e64 s[28:29], s28, v195
	s_and_b64 s[30:31], s[34:35], s[30:31]
	v_cmp_gt_i32_e64 s[18:19], s18, v195
	v_cndmask_b32_e64 v70, v70, v190, s[24:25]
	s_and_b64 s[20:21], s[22:23], s[20:21]
	s_movk_i32 s24, 0x68
	v_cmp_gt_i32_e64 s[26:27], s26, v195
	s_and_b64 s[28:29], s[30:31], s[28:29]
	v_cndmask_b32_e32 v50, v50, v190, vcc
	v_cmp_gt_i32_e32 vcc, 64, v195
	v_cndmask_b32_e64 v69, v69, v190, s[22:23]
	s_and_b64 s[18:19], s[20:21], s[18:19]
	s_movk_i32 s22, 0x63
	v_cmp_gt_i32_e64 s[24:25], s24, v195
	s_and_b64 s[26:27], s[28:29], s[26:27]
	v_cndmask_b32_e64 v68, v68, v190, s[20:21]
	v_cndmask_b32_e64 v67, v67, v190, s[18:19]
	s_and_b64 vcc, s[18:19], vcc
	s_movk_i32 s18, 0x60
	s_movk_i32 s20, 0x62
	v_cmp_gt_i32_e64 s[22:23], s22, v195
	s_and_b64 s[24:25], s[26:27], s[24:25]
	v_cndmask_b32_e32 v66, v66, v190, vcc
	v_cmp_gt_i32_e32 vcc, s18, v195
	s_movk_i32 s18, 0x61
	v_cmp_gt_i32_e64 s[20:21], s20, v195
	s_and_b64 s[22:23], s[24:25], s[22:23]
	v_cmp_gt_i32_e64 s[18:19], s18, v195
	s_and_b64 s[20:21], s[22:23], s[20:21]
	s_and_b64 s[18:19], s[20:21], s[18:19]
	s_and_b64 vcc, s[18:19], vcc
	v_cndmask_b32_e64 v113, v113, v190, s[48:49]
	v_cndmask_b32_e64 v112, v112, v190, s[46:47]
	v_cndmask_b32_e64 v111, v111, v190, s[44:45]
	v_cndmask_b32_e64 v110, v110, v190, s[42:43]
	v_cndmask_b32_e64 v109, v109, v190, s[40:41]
	v_cndmask_b32_e64 v108, v108, v190, s[38:39]
	v_cndmask_b32_e64 v107, v107, v190, s[36:37]
	v_cndmask_b32_e64 v106, v106, v190, s[34:35]
	v_cndmask_b32_e64 v105, v105, v190, s[30:31]
	v_cndmask_b32_e64 v104, v104, v190, s[28:29]
	v_cndmask_b32_e64 v103, v103, v190, s[26:27]
	v_cndmask_b32_e64 v102, v102, v190, s[24:25]
	v_cndmask_b32_e64 v101, v101, v190, s[22:23]
	v_cndmask_b32_e64 v100, v100, v190, s[20:21]
	v_cndmask_b32_e64 v99, v99, v190, s[18:19]
	v_cndmask_b32_e32 v98, v98, v190, vcc
